# code placement: .p2align 6 before the six main GEMM K-loop heads (G1, G2a, G2b, G3, UP, G6a)
# speedup vs baseline: 1.0013x; 1.0013x over previous
; template <class Epi, class Sched, bool ALIGN_EPI = false, bool SP2 = false>
; __device__ __forceinline__ void gemm_phase(PG8_LAS unsigned char* lds, const Gemm g, const Sched& S, const Epi& E, const int tid_in) {
;     ...
;         const bool has_next = S.next(ui + 1, nxt);
;         const char* nA = has_next ? (const char*)g.A + (size_t)nxt.pm * tstepA : cA; const char* nB = has_next ? (const char*)g.Bt + (size_t)nxt.pn * tstepB : cB;
;         for (int t = 0; t < nt; t += 2) {
;             const bool last = (t == nt - 2);
;             const char* a1 = cA + (size_t)(t + 1) * kstep;
;             const char* a2 = last ? nA : cA + (size_t)(t + 2) * kstep; const char* b2 = last ? nB : cB + (size_t)(t + 2) * kstep;
;     ...
;         for (int a = 0; a < 2; ++a)
; #pragma unroll
;             for (int b = 0; b < 2; ++b)
; #pragma unroll
;                 for (int m = 0; m < 4; ++m)
; #pragma unroll
;                     for (int n = 0; n < 2; ++n) acc[a][b][m][n] = (f32x4){zf_, zf_, zf_, zf_};
;         cur = nxt; cA = nA; cB = nB; ++ui;
.LBB0_285:
	s_ashr_i32 s15, s14, 31
	s_lshl_b64 s[16:17], s[14:15], 19
	s_add_u32 s16, s4, s16
	s_addc_u32 s17, s5, s17
	s_and_b64 s[18:19], s[6:7], exec
	s_cselect_b32 s15, s17, s21
	s_cselect_b32 s42, s16, s20
	s_ashr_i32 s13, s12, 31
	s_lshl_b64 s[18:19], s[12:13], 19
	s_add_u32 s18, s26, s18
	s_addc_u32 s19, s27, s19
	s_and_b64 s[24:25], s[6:7], exec
	s_cselect_b32 s13, s19, s23
	s_cselect_b32 s43, s18, s22
	s_add_u32 s20, s20, 0x40080
	s_addc_u32 s21, s21, 0
	s_add_u32 s44, s22, 0x100
	s_addc_u32 s45, s23, 0
	s_mov_b32 s46, -2
	v_mov_b32_e32 v0, v99
	v_mov_b32_e32 v1, v99
	v_mov_b32_e32 v2, v99
	v_mov_b32_e32 v3, v99
	v_mov_b32_e32 v4, v99
	v_mov_b32_e32 v5, v99
	v_mov_b32_e32 v6, v99
	v_mov_b32_e32 v7, v99
	v_mov_b32_e32 v8, v99
	v_mov_b32_e32 v9, v99
	v_mov_b32_e32 v10, v99
	v_mov_b32_e32 v11, v99
	v_mov_b32_e32 v16, v99
	v_mov_b32_e32 v17, v99
	v_mov_b32_e32 v18, v99
	v_mov_b32_e32 v19, v99
	v_mov_b32_e32 v24, v99
	v_mov_b32_e32 v25, v99
	v_mov_b32_e32 v26, v99
	v_mov_b32_e32 v27, v99
	v_mov_b32_e32 v32, v99
	v_mov_b32_e32 v33, v99
	v_mov_b32_e32 v34, v99
	v_mov_b32_e32 v35, v99
	v_mov_b32_e32 v40, v99
	v_mov_b32_e32 v41, v99
	v_mov_b32_e32 v42, v99
	v_mov_b32_e32 v43, v99
	v_mov_b32_e32 v48, v99
	v_mov_b32_e32 v49, v99
	v_mov_b32_e32 v50, v99
	v_mov_b32_e32 v51, v99
	v_mov_b32_e32 v12, v99
	v_mov_b32_e32 v13, v99
	v_mov_b32_e32 v14, v99
	v_mov_b32_e32 v15, v99
	v_mov_b32_e32 v20, v99
	v_mov_b32_e32 v21, v99
	v_mov_b32_e32 v22, v99
	v_mov_b32_e32 v23, v99
	v_mov_b32_e32 v28, v99
	v_mov_b32_e32 v29, v99
	v_mov_b32_e32 v30, v99
	v_mov_b32_e32 v31, v99
	v_mov_b32_e32 v36, v99
	v_mov_b32_e32 v37, v99
	v_mov_b32_e32 v38, v99
	v_mov_b32_e32 v39, v99
	v_mov_b32_e32 v44, v99
	v_mov_b32_e32 v45, v99
	v_mov_b32_e32 v46, v99
	v_mov_b32_e32 v47, v99
	v_mov_b32_e32 v52, v99
	v_mov_b32_e32 v53, v99
	v_mov_b32_e32 v54, v99
	v_mov_b32_e32 v55, v99
	v_mov_b32_e32 v56, v99
	v_mov_b32_e32 v57, v99
	v_mov_b32_e32 v58, v99
	v_mov_b32_e32 v59, v99
	v_mov_b32_e32 v60, v99
	v_mov_b32_e32 v61, v99
	v_mov_b32_e32 v62, v99
	v_mov_b32_e32 v63, v99
	v_mov_b32_e32 v64, v99
	v_mov_b32_e32 v65, v99
	v_mov_b32_e32 v66, v99
	v_mov_b32_e32 v67, v99
	v_mov_b32_e32 v68, v99
	v_mov_b32_e32 v69, v99
	v_mov_b32_e32 v70, v99
	v_mov_b32_e32 v71, v99
	v_mov_b32_e32 v72, v99
	v_mov_b32_e32 v73, v99
	v_mov_b32_e32 v74, v99
	v_mov_b32_e32 v75, v99
	v_mov_b32_e32 v80, v99
	v_mov_b32_e32 v81, v99
	v_mov_b32_e32 v82, v99
	v_mov_b32_e32 v83, v99
	v_mov_b32_e32 v100, v99
	v_mov_b32_e32 v101, v99
	v_mov_b32_e32 v102, v99
	v_mov_b32_e32 v103, v99
	v_mov_b32_e32 v104, v99
	v_mov_b32_e32 v105, v99
	v_mov_b32_e32 v106, v99
	v_mov_b32_e32 v107, v99
	v_mov_b32_e32 v116, v99
	v_mov_b32_e32 v117, v99
	v_mov_b32_e32 v118, v99
	v_mov_b32_e32 v119, v99
	v_mov_b32_e32 v120, v99
	v_mov_b32_e32 v121, v99
	v_mov_b32_e32 v122, v99
	v_mov_b32_e32 v123, v99
	v_mov_b32_e32 v76, v99
	v_mov_b32_e32 v77, v99
	v_mov_b32_e32 v78, v99
	v_mov_b32_e32 v79, v99
	v_mov_b32_e32 v84, v99
	v_mov_b32_e32 v85, v99
	v_mov_b32_e32 v86, v99
	v_mov_b32_e32 v87, v99
	v_mov_b32_e32 v88, v99
	v_mov_b32_e32 v89, v99
	v_mov_b32_e32 v90, v99
	v_mov_b32_e32 v91, v99
	v_mov_b32_e32 v92, v99
	v_mov_b32_e32 v93, v99
	v_mov_b32_e32 v94, v99
	v_mov_b32_e32 v95, v99
	v_mov_b32_e32 v108, v99
	v_mov_b32_e32 v109, v99
	v_mov_b32_e32 v110, v99
	v_mov_b32_e32 v111, v99
	v_mov_b32_e32 v112, v99
	v_mov_b32_e32 v113, v99
	v_mov_b32_e32 v114, v99
	v_mov_b32_e32 v115, v99
	v_mov_b32_e32 v124, v99
	v_mov_b32_e32 v125, v99
	v_mov_b32_e32 v126, v99
	v_mov_b32_e32 v127, v99
	v_mov_b32_e32 v128, v99
	v_mov_b32_e32 v129, v99
	v_mov_b32_e32 v130, v99
	v_mov_b32_e32 v131, v99
	.p2align	6

; template <class Epi, class Sched, bool ALIGN_EPI = false, bool SP2 = false>
; __device__ __forceinline__ void gemm_phase(PG8_LAS unsigned char* lds, const Gemm g, const Sched& S, const Epi& E, const int tid_in) {
;     ...
;         const bool has_next = S.next(ui + 1, nxt);
;         const char* nA = has_next ? (const char*)g.A + (size_t)nxt.pm * tstepA : cA; const char* nB = has_next ? (const char*)g.Bt + (size_t)nxt.pn * tstepB : cB;
;         for (int t = 0; t < nt; t += 2) {
;             const bool last = (t == nt - 2);
;             const char* a1 = cA + (size_t)(t + 1) * kstep;
;             const char* a2 = last ? nA : cA + (size_t)(t + 2) * kstep; const char* b2 = last ? nB : cB + (size_t)(t + 2) * kstep;
;     ...
;         for (int a = 0; a < 2; ++a)
; #pragma unroll
;             for (int b = 0; b < 2; ++b)
; #pragma unroll
;                 for (int m = 0; m < 4; ++m)
; #pragma unroll
;                     for (int n = 0; n < 2; ++n) acc[a][b][m][n] = (f32x4){zf_, zf_, zf_, zf_};
;         cur = nxt; cA = nA; cB = nB; ++ui;
.LBB0_592:
	s_ashr_i32 s17, s16, 31
	s_lshl_b64 s[20:21], s[16:17], 18
	s_add_u32 s20, s30, s20
	s_addc_u32 s21, s31, s21
	s_and_b64 s[0:1], s[0:1], exec
	s_cselect_b32 s17, s21, s25
	s_cselect_b32 s47, s20, s24
	s_add_u32 s48, s24, 0x100
	s_addc_u32 s49, s25, 0
	s_mov_b32 s52, -2
	v_mov_b32_e32 v0, v99
	v_mov_b32_e32 v1, v99
	v_mov_b32_e32 v2, v99
	v_mov_b32_e32 v3, v99
	v_mov_b32_e32 v4, v99
	v_mov_b32_e32 v5, v99
	v_mov_b32_e32 v6, v99
	v_mov_b32_e32 v7, v99
	v_mov_b32_e32 v16, v99
	v_mov_b32_e32 v17, v99
	v_mov_b32_e32 v18, v99
	v_mov_b32_e32 v19, v99
	v_mov_b32_e32 v20, v99
	v_mov_b32_e32 v21, v99
	v_mov_b32_e32 v22, v99
	v_mov_b32_e32 v23, v99
	v_mov_b32_e32 v32, v99
	v_mov_b32_e32 v33, v99
	v_mov_b32_e32 v34, v99
	v_mov_b32_e32 v35, v99
	v_mov_b32_e32 v36, v99
	v_mov_b32_e32 v37, v99
	v_mov_b32_e32 v38, v99
	v_mov_b32_e32 v39, v99
	v_mov_b32_e32 v48, v99
	v_mov_b32_e32 v49, v99
	v_mov_b32_e32 v50, v99
	v_mov_b32_e32 v51, v99
	v_mov_b32_e32 v52, v99
	v_mov_b32_e32 v53, v99
	v_mov_b32_e32 v54, v99
	v_mov_b32_e32 v55, v99
	v_mov_b32_e32 v8, v99
	v_mov_b32_e32 v9, v99
	v_mov_b32_e32 v10, v99
	v_mov_b32_e32 v11, v99
	v_mov_b32_e32 v12, v99
	v_mov_b32_e32 v13, v99
	v_mov_b32_e32 v14, v99
	v_mov_b32_e32 v15, v99
	v_mov_b32_e32 v24, v99
	v_mov_b32_e32 v25, v99
	v_mov_b32_e32 v26, v99
	v_mov_b32_e32 v27, v99
	v_mov_b32_e32 v28, v99
	v_mov_b32_e32 v29, v99
	v_mov_b32_e32 v30, v99
	v_mov_b32_e32 v31, v99
	v_mov_b32_e32 v40, v99
	v_mov_b32_e32 v41, v99
	v_mov_b32_e32 v42, v99
	v_mov_b32_e32 v43, v99
	v_mov_b32_e32 v44, v99
	v_mov_b32_e32 v45, v99
	v_mov_b32_e32 v46, v99
	v_mov_b32_e32 v47, v99
	v_mov_b32_e32 v56, v99
	v_mov_b32_e32 v57, v99
	v_mov_b32_e32 v58, v99
	v_mov_b32_e32 v59, v99
	v_mov_b32_e32 v60, v99
	v_mov_b32_e32 v61, v99
	v_mov_b32_e32 v62, v99
	v_mov_b32_e32 v63, v99
	v_mov_b32_e32 v64, v99
	v_mov_b32_e32 v65, v99
	v_mov_b32_e32 v66, v99
	v_mov_b32_e32 v67, v99
	v_mov_b32_e32 v68, v99
	v_mov_b32_e32 v69, v99
	v_mov_b32_e32 v70, v99
	v_mov_b32_e32 v71, v99
	v_mov_b32_e32 v80, v99
	v_mov_b32_e32 v81, v99
	v_mov_b32_e32 v82, v99
	v_mov_b32_e32 v83, v99
	v_mov_b32_e32 v84, v99
	v_mov_b32_e32 v85, v99
	v_mov_b32_e32 v86, v99
	v_mov_b32_e32 v87, v99
	s_waitcnt vmcnt(0)
	v_mov_b32_e32 v100, v99
	v_mov_b32_e32 v101, v99
	v_mov_b32_e32 v102, v99
	v_mov_b32_e32 v103, v99
	v_mov_b32_e32 v104, v99
	v_mov_b32_e32 v105, v99
	v_mov_b32_e32 v106, v99
	v_mov_b32_e32 v107, v99
	v_mov_b32_e32 v124, v99
	v_mov_b32_e32 v125, v99
	v_mov_b32_e32 v126, v99
	v_mov_b32_e32 v127, v99
	v_mov_b32_e32 v132, v99
	v_mov_b32_e32 v133, v99
	v_mov_b32_e32 v134, v99
	v_mov_b32_e32 v135, v99
	v_mov_b32_e32 v72, v99
	v_mov_b32_e32 v73, v99
	v_mov_b32_e32 v74, v99
	v_mov_b32_e32 v75, v99
	v_mov_b32_e32 v76, v99
	v_mov_b32_e32 v77, v99
	v_mov_b32_e32 v78, v99
	v_mov_b32_e32 v79, v99
	v_mov_b32_e32 v88, v99
	v_mov_b32_e32 v89, v99
	v_mov_b32_e32 v90, v99
	v_mov_b32_e32 v91, v99
	v_mov_b32_e32 v92, v99
	v_mov_b32_e32 v93, v99
	v_mov_b32_e32 v94, v99
	v_mov_b32_e32 v95, v99
	v_mov_b32_e32 v108, v99
	v_mov_b32_e32 v109, v99
	v_mov_b32_e32 v110, v99
	v_mov_b32_e32 v111, v99
	v_mov_b32_e32 v120, v99
	v_mov_b32_e32 v121, v99
	v_mov_b32_e32 v122, v99
	v_mov_b32_e32 v123, v99
	v_mov_b32_e32 v148, v99
	v_mov_b32_e32 v149, v99
	v_mov_b32_e32 v150, v99
	v_mov_b32_e32 v151, v99
	v_mov_b32_e32 v152, v99
	v_mov_b32_e32 v153, v99
	v_mov_b32_e32 v154, v99
	v_mov_b32_e32 v155, v99
	.p2align	6

; template <class Epi, class Sched, bool ALIGN_EPI = false, bool SP2 = false>
; __device__ __forceinline__ void gemm_phase(PG8_LAS unsigned char* lds, const Gemm g, const Sched& S, const Epi& E, const int tid_in) {
;     ...
;         const bool has_next = S.next(ui + 1, nxt);
;         const char* nA = has_next ? (const char*)g.A + (size_t)nxt.pm * tstepA : cA; const char* nB = has_next ? (const char*)g.Bt + (size_t)nxt.pn * tstepB : cB;
;         for (int t = 0; t < nt; t += 2) {
;             const bool last = (t == nt - 2);
;             const char* a1 = cA + (size_t)(t + 1) * kstep;
;             const char* a2 = last ? nA : cA + (size_t)(t + 2) * kstep; const char* b2 = last ? nB : cB + (size_t)(t + 2) * kstep;
;     ...
;         for (int a = 0; a < 2; ++a)
; #pragma unroll
;             for (int b = 0; b < 2; ++b)
; #pragma unroll
;                 for (int m = 0; m < 4; ++m)
; #pragma unroll
;                     for (int n = 0; n < 2; ++n) acc[a][b][m][n] = (f32x4){zf_, zf_, zf_, zf_};
;         cur = nxt; cA = nA; cB = nB; ++ui;
.LBB0_614:
	s_ashr_i32 s15, s14, 31
	s_lshl_b64 s[18:19], s[14:15], 18
	s_add_u32 s18, s28, s18
	s_addc_u32 s19, s29, s19
	s_and_b64 s[0:1], s[0:1], exec
	s_cselect_b32 s15, s19, s23
	s_cselect_b32 s45, s18, s22
	s_add_u32 s46, s22, 0x100
	s_addc_u32 s47, s23, 0
	s_mov_b32 s48, -2
	v_mov_b32_e32 v0, v99
	v_mov_b32_e32 v1, v99
	v_mov_b32_e32 v2, v99
	v_mov_b32_e32 v3, v99
	v_mov_b32_e32 v4, v99
	v_mov_b32_e32 v5, v99
	v_mov_b32_e32 v6, v99
	v_mov_b32_e32 v7, v99
	v_mov_b32_e32 v16, v99
	v_mov_b32_e32 v17, v99
	v_mov_b32_e32 v18, v99
	v_mov_b32_e32 v19, v99
	v_mov_b32_e32 v20, v99
	v_mov_b32_e32 v21, v99
	v_mov_b32_e32 v22, v99
	v_mov_b32_e32 v23, v99
	v_mov_b32_e32 v32, v99
	v_mov_b32_e32 v33, v99
	v_mov_b32_e32 v34, v99
	v_mov_b32_e32 v35, v99
	v_mov_b32_e32 v36, v99
	v_mov_b32_e32 v37, v99
	v_mov_b32_e32 v38, v99
	v_mov_b32_e32 v39, v99
	v_mov_b32_e32 v48, v99
	v_mov_b32_e32 v49, v99
	v_mov_b32_e32 v50, v99
	v_mov_b32_e32 v51, v99
	v_mov_b32_e32 v52, v99
	v_mov_b32_e32 v53, v99
	v_mov_b32_e32 v54, v99
	v_mov_b32_e32 v55, v99
	v_mov_b32_e32 v8, v99
	v_mov_b32_e32 v9, v99
	v_mov_b32_e32 v10, v99
	v_mov_b32_e32 v11, v99
	v_mov_b32_e32 v12, v99
	v_mov_b32_e32 v13, v99
	v_mov_b32_e32 v14, v99
	v_mov_b32_e32 v15, v99
	v_mov_b32_e32 v24, v99
	v_mov_b32_e32 v25, v99
	v_mov_b32_e32 v26, v99
	v_mov_b32_e32 v27, v99
	v_mov_b32_e32 v28, v99
	v_mov_b32_e32 v29, v99
	v_mov_b32_e32 v30, v99
	v_mov_b32_e32 v31, v99
	v_mov_b32_e32 v40, v99
	v_mov_b32_e32 v41, v99
	v_mov_b32_e32 v42, v99
	v_mov_b32_e32 v43, v99
	v_mov_b32_e32 v44, v99
	v_mov_b32_e32 v45, v99
	v_mov_b32_e32 v46, v99
	v_mov_b32_e32 v47, v99
	v_mov_b32_e32 v56, v99
	v_mov_b32_e32 v57, v99
	v_mov_b32_e32 v58, v99
	v_mov_b32_e32 v59, v99
	v_mov_b32_e32 v60, v99
	v_mov_b32_e32 v61, v99
	v_mov_b32_e32 v62, v99
	v_mov_b32_e32 v63, v99
	v_mov_b32_e32 v64, v99
	v_mov_b32_e32 v65, v99
	v_mov_b32_e32 v66, v99
	v_mov_b32_e32 v67, v99
	v_mov_b32_e32 v68, v99
	v_mov_b32_e32 v69, v99
	v_mov_b32_e32 v70, v99
	v_mov_b32_e32 v71, v99
	v_mov_b32_e32 v80, v99
	v_mov_b32_e32 v81, v99
	v_mov_b32_e32 v82, v99
	v_mov_b32_e32 v83, v99
	v_mov_b32_e32 v84, v99
	v_mov_b32_e32 v85, v99
	v_mov_b32_e32 v86, v99
	v_mov_b32_e32 v87, v99
	s_waitcnt vmcnt(0)
	v_mov_b32_e32 v100, v99
	v_mov_b32_e32 v101, v99
	v_mov_b32_e32 v102, v99
	v_mov_b32_e32 v103, v99
	v_mov_b32_e32 v104, v99
	v_mov_b32_e32 v105, v99
	v_mov_b32_e32 v106, v99
	v_mov_b32_e32 v107, v99
	v_mov_b32_e32 v116, v99
	v_mov_b32_e32 v117, v99
	v_mov_b32_e32 v118, v99
	v_mov_b32_e32 v119, v99
	v_mov_b32_e32 v128, v99
	v_mov_b32_e32 v129, v99
	v_mov_b32_e32 v130, v99
	v_mov_b32_e32 v131, v99
	v_mov_b32_e32 v72, v99
	v_mov_b32_e32 v73, v99
	v_mov_b32_e32 v74, v99
	v_mov_b32_e32 v75, v99
	v_mov_b32_e32 v76, v99
	v_mov_b32_e32 v77, v99
	v_mov_b32_e32 v78, v99
	v_mov_b32_e32 v79, v99
	v_mov_b32_e32 v88, v99
	v_mov_b32_e32 v89, v99
	v_mov_b32_e32 v90, v99
	v_mov_b32_e32 v91, v99
	v_mov_b32_e32 v92, v99
	v_mov_b32_e32 v93, v99
	v_mov_b32_e32 v94, v99
	v_mov_b32_e32 v95, v99
	v_mov_b32_e32 v108, v99
	v_mov_b32_e32 v109, v99
	v_mov_b32_e32 v110, v99
	v_mov_b32_e32 v111, v99
	v_mov_b32_e32 v112, v99
	v_mov_b32_e32 v113, v99
	v_mov_b32_e32 v114, v99
	v_mov_b32_e32 v115, v99
	v_mov_b32_e32 v148, v99
	v_mov_b32_e32 v149, v99
	v_mov_b32_e32 v150, v99
	v_mov_b32_e32 v151, v99
	v_mov_b32_e32 v160, v99
	v_mov_b32_e32 v161, v99
	v_mov_b32_e32 v162, v99
	v_mov_b32_e32 v163, v99
	.p2align	6

; template <class Epi, class Sched, bool ALIGN_EPI = false, bool SP2 = false>
; __device__ __forceinline__ void gemm_phase(PG8_LAS unsigned char* lds, const Gemm g, const Sched& S, const Epi& E, const int tid_in) {
;     ...
;         const bool has_next = S.next(ui + 1, nxt);
;         const char* nA = has_next ? (const char*)g.A + (size_t)nxt.pm * tstepA : cA; const char* nB = has_next ? (const char*)g.Bt + (size_t)nxt.pn * tstepB : cB;
;         for (int t = 0; t < nt; t += 2) {
;             const bool last = (t == nt - 2);
;             const char* a1 = cA + (size_t)(t + 1) * kstep;
;             const char* a2 = last ? nA : cA + (size_t)(t + 2) * kstep; const char* b2 = last ? nB : cB + (size_t)(t + 2) * kstep;
;     ...
;         for (int a = 0; a < 2; ++a)
; #pragma unroll
;             for (int b = 0; b < 2; ++b)
; #pragma unroll
;                 for (int m = 0; m < 4; ++m)
; #pragma unroll
;                     for (int n = 0; n < 2; ++n) acc[a][b][m][n] = (f32x4){zf_, zf_, zf_, zf_};
;         cur = nxt; cA = nA; cB = nB; ++ui;
.LBB0_688:
	s_ashr_i32 s23, s22, 31
	s_lshl_b64 s[24:25], s[22:23], 19
	s_add_u32 s24, s39, s24
	s_addc_u32 s25, s40, s25
	s_and_b64 s[26:27], s[8:9], exec
	s_cselect_b32 s23, s25, s29
	s_cselect_b32 s55, s24, s28
	s_ashr_i32 s21, s20, 31
	s_lshl_b64 s[26:27], s[20:21], 19
	s_add_u32 s26, s41, s26
	s_addc_u32 s27, s42, s27
	s_and_b64 s[34:35], s[8:9], exec
	s_cselect_b32 s21, s27, s31
	s_cselect_b32 s56, s26, s30
	s_add_u32 s28, s28, 0x40080
	s_addc_u32 s29, s29, 0
	s_add_u32 s57, s30, 0x100
	s_addc_u32 s60, s31, 0
	s_mov_b32 s61, -2
	v_mov_b32_e32 v0, v99
	v_mov_b32_e32 v1, v99
	v_mov_b32_e32 v2, v99
	v_mov_b32_e32 v3, v99
	v_mov_b32_e32 v4, v99
	v_mov_b32_e32 v5, v99
	v_mov_b32_e32 v6, v99
	v_mov_b32_e32 v7, v99
	v_mov_b32_e32 v16, v99
	v_mov_b32_e32 v17, v99
	v_mov_b32_e32 v18, v99
	v_mov_b32_e32 v19, v99
	v_mov_b32_e32 v20, v99
	v_mov_b32_e32 v21, v99
	v_mov_b32_e32 v22, v99
	v_mov_b32_e32 v23, v99
	v_mov_b32_e32 v32, v99
	v_mov_b32_e32 v33, v99
	v_mov_b32_e32 v34, v99
	v_mov_b32_e32 v35, v99
	v_mov_b32_e32 v36, v99
	v_mov_b32_e32 v37, v99
	v_mov_b32_e32 v38, v99
	v_mov_b32_e32 v39, v99
	v_mov_b32_e32 v48, v99
	v_mov_b32_e32 v49, v99
	v_mov_b32_e32 v50, v99
	v_mov_b32_e32 v51, v99
	v_mov_b32_e32 v52, v99
	v_mov_b32_e32 v53, v99
	v_mov_b32_e32 v54, v99
	v_mov_b32_e32 v55, v99
	v_mov_b32_e32 v8, v99
	v_mov_b32_e32 v9, v99
	v_mov_b32_e32 v10, v99
	v_mov_b32_e32 v11, v99
	v_mov_b32_e32 v12, v99
	v_mov_b32_e32 v13, v99
	v_mov_b32_e32 v14, v99
	v_mov_b32_e32 v15, v99
	v_mov_b32_e32 v24, v99
	v_mov_b32_e32 v25, v99
	v_mov_b32_e32 v26, v99
	v_mov_b32_e32 v27, v99
	v_mov_b32_e32 v28, v99
	v_mov_b32_e32 v29, v99
	v_mov_b32_e32 v30, v99
	v_mov_b32_e32 v31, v99
	v_mov_b32_e32 v40, v99
	v_mov_b32_e32 v41, v99
	v_mov_b32_e32 v42, v99
	v_mov_b32_e32 v43, v99
	v_mov_b32_e32 v44, v99
	v_mov_b32_e32 v45, v99
	v_mov_b32_e32 v46, v99
	v_mov_b32_e32 v47, v99
	v_mov_b32_e32 v56, v99
	v_mov_b32_e32 v57, v99
	v_mov_b32_e32 v58, v99
	v_mov_b32_e32 v59, v99
	v_mov_b32_e32 v60, v99
	v_mov_b32_e32 v61, v99
	v_mov_b32_e32 v62, v99
	v_mov_b32_e32 v63, v99
	v_mov_b32_e32 v64, v99
	v_mov_b32_e32 v65, v99
	v_mov_b32_e32 v66, v99
	v_mov_b32_e32 v67, v99
	v_mov_b32_e32 v68, v99
	v_mov_b32_e32 v69, v99
	v_mov_b32_e32 v70, v99
	v_mov_b32_e32 v71, v99
	v_mov_b32_e32 v80, v99
	v_mov_b32_e32 v81, v99
	v_mov_b32_e32 v82, v99
	v_mov_b32_e32 v83, v99
	v_mov_b32_e32 v84, v99
	v_mov_b32_e32 v85, v99
	v_mov_b32_e32 v86, v99
	v_mov_b32_e32 v87, v99
	s_waitcnt vmcnt(0)
	v_mov_b32_e32 v100, v99
	v_mov_b32_e32 v101, v99
	v_mov_b32_e32 v102, v99
	v_mov_b32_e32 v103, v99
	v_mov_b32_e32 v104, v99
	v_mov_b32_e32 v105, v99
	v_mov_b32_e32 v106, v99
	v_mov_b32_e32 v107, v99
	v_mov_b32_e32 v116, v99
	v_mov_b32_e32 v117, v99
	v_mov_b32_e32 v118, v99
	v_mov_b32_e32 v119, v99
	v_mov_b32_e32 v120, v99
	v_mov_b32_e32 v121, v99
	v_mov_b32_e32 v122, v99
	v_mov_b32_e32 v123, v99
	v_mov_b32_e32 v72, v99
	v_mov_b32_e32 v73, v99
	v_mov_b32_e32 v74, v99
	v_mov_b32_e32 v75, v99
	v_mov_b32_e32 v76, v99
	v_mov_b32_e32 v77, v99
	v_mov_b32_e32 v78, v99
	v_mov_b32_e32 v79, v99
	v_mov_b32_e32 v88, v99
	v_mov_b32_e32 v89, v99
	v_mov_b32_e32 v90, v99
	v_mov_b32_e32 v91, v99
	v_mov_b32_e32 v92, v99
	v_mov_b32_e32 v93, v99
	v_mov_b32_e32 v94, v99
	v_mov_b32_e32 v95, v99
	v_mov_b32_e32 v108, v99
	v_mov_b32_e32 v109, v99
	v_mov_b32_e32 v110, v99
	v_mov_b32_e32 v111, v99
	v_mov_b32_e32 v112, v99
	v_mov_b32_e32 v113, v99
	v_mov_b32_e32 v114, v99
	v_mov_b32_e32 v115, v99
	v_mov_b32_e32 v124, v99
	v_mov_b32_e32 v125, v99
	v_mov_b32_e32 v126, v99
	v_mov_b32_e32 v127, v99
	v_mov_b32_e32 v128, v99
	v_mov_b32_e32 v129, v99
	v_mov_b32_e32 v130, v99
	v_mov_b32_e32 v131, v99
	.p2align	6

; template <class Epi, class Sched, bool ALIGN_EPI = false, bool SP2 = false>
; __device__ __forceinline__ void gemm_phase(PG8_LAS unsigned char* lds, const Gemm g, const Sched& S, const Epi& E, const int tid_in) {
;     ...
;         const bool has_next = S.next(ui + 1, nxt);
;         const char* nA = has_next ? (const char*)g.A + (size_t)nxt.pm * tstepA : cA; const char* nB = has_next ? (const char*)g.Bt + (size_t)nxt.pn * tstepB : cB;
;         for (int t = 0; t < nt; t += 2) {
;             const bool last = (t == nt - 2);
;             const char* a1 = cA + (size_t)(t + 1) * kstep;
;             const char* a2 = last ? nA : cA + (size_t)(t + 2) * kstep; const char* b2 = last ? nB : cB + (size_t)(t + 2) * kstep;
;     ...
;         for (int a = 0; a < 2; ++a)
; #pragma unroll
;             for (int b = 0; b < 2; ++b)
; #pragma unroll
;                 for (int m = 0; m < 4; ++m)
; #pragma unroll
;                     for (int n = 0; n < 2; ++n) acc[a][b][m][n] = (f32x4){zf_, zf_, zf_, zf_};
;         cur = nxt; cA = nA; cB = nB; ++ui;
.LBB0_848:
	s_ashr_i32 s23, s22, 31
	s_lshl_b64 s[24:25], s[22:23], 19
	s_add_u32 s24, s36, s24
	s_addc_u32 s25, s37, s25
	s_and_b64 s[26:27], s[8:9], exec
	s_cselect_b32 s23, s25, s29
	s_cselect_b32 s53, s24, s28
	s_ashr_i32 s21, s20, 31
	s_lshl_b64 s[26:27], s[20:21], 19
	s_add_u32 s26, s38, s26
	s_addc_u32 s27, s39, s27
	s_and_b64 s[34:35], s[8:9], exec
	s_cselect_b32 s21, s27, s31
	s_cselect_b32 s54, s26, s30
	s_add_u32 s28, s28, 0x40080
	s_addc_u32 s29, s29, 0
	s_add_u32 s55, s30, 0x100
	s_addc_u32 s56, s31, 0
	s_mov_b32 s57, -2
	v_mov_b32_e32 v0, v99
	v_mov_b32_e32 v1, v99
	v_mov_b32_e32 v2, v99
	v_mov_b32_e32 v3, v99
	v_mov_b32_e32 v4, v99
	v_mov_b32_e32 v5, v99
	v_mov_b32_e32 v6, v99
	v_mov_b32_e32 v7, v99
	v_mov_b32_e32 v8, v99
	v_mov_b32_e32 v9, v99
	v_mov_b32_e32 v10, v99
	v_mov_b32_e32 v11, v99
	v_mov_b32_e32 v16, v99
	v_mov_b32_e32 v17, v99
	v_mov_b32_e32 v18, v99
	v_mov_b32_e32 v19, v99
	v_mov_b32_e32 v24, v99
	v_mov_b32_e32 v25, v99
	v_mov_b32_e32 v26, v99
	v_mov_b32_e32 v27, v99
	v_mov_b32_e32 v32, v99
	v_mov_b32_e32 v33, v99
	v_mov_b32_e32 v34, v99
	v_mov_b32_e32 v35, v99
	v_mov_b32_e32 v40, v99
	v_mov_b32_e32 v41, v99
	v_mov_b32_e32 v42, v99
	v_mov_b32_e32 v43, v99
	v_mov_b32_e32 v48, v99
	v_mov_b32_e32 v49, v99
	v_mov_b32_e32 v50, v99
	v_mov_b32_e32 v51, v99
	v_mov_b32_e32 v12, v99
	v_mov_b32_e32 v13, v99
	v_mov_b32_e32 v14, v99
	v_mov_b32_e32 v15, v99
	v_mov_b32_e32 v20, v99
	v_mov_b32_e32 v21, v99
	v_mov_b32_e32 v22, v99
	v_mov_b32_e32 v23, v99
	v_mov_b32_e32 v28, v99
	v_mov_b32_e32 v29, v99
	v_mov_b32_e32 v30, v99
	v_mov_b32_e32 v31, v99
	v_mov_b32_e32 v36, v99
	v_mov_b32_e32 v37, v99
	v_mov_b32_e32 v38, v99
	v_mov_b32_e32 v39, v99
	v_mov_b32_e32 v44, v99
	v_mov_b32_e32 v45, v99
	v_mov_b32_e32 v46, v99
	v_mov_b32_e32 v47, v99
	v_mov_b32_e32 v52, v99
	v_mov_b32_e32 v53, v99
	v_mov_b32_e32 v54, v99
	v_mov_b32_e32 v55, v99
	v_mov_b32_e32 v56, v99
	v_mov_b32_e32 v57, v99
	v_mov_b32_e32 v58, v99
	v_mov_b32_e32 v59, v99
	v_mov_b32_e32 v60, v99
	v_mov_b32_e32 v61, v99
	v_mov_b32_e32 v62, v99
	v_mov_b32_e32 v63, v99
	v_mov_b32_e32 v64, v99
	v_mov_b32_e32 v65, v99
	v_mov_b32_e32 v66, v99
	v_mov_b32_e32 v67, v99
	v_mov_b32_e32 v68, v99
	v_mov_b32_e32 v69, v99
	v_mov_b32_e32 v70, v99
	v_mov_b32_e32 v71, v99
	v_mov_b32_e32 v80, v99
	v_mov_b32_e32 v81, v99
	v_mov_b32_e32 v82, v99
	v_mov_b32_e32 v83, v99
	v_mov_b32_e32 v84, v99
	v_mov_b32_e32 v85, v99
	v_mov_b32_e32 v86, v99
	v_mov_b32_e32 v87, v99
	v_mov_b32_e32 v100, v99
	v_mov_b32_e32 v101, v99
	v_mov_b32_e32 v102, v99
	v_mov_b32_e32 v103, v99
	v_mov_b32_e32 v104, v99
	v_mov_b32_e32 v105, v99
	v_mov_b32_e32 v106, v99
	v_mov_b32_e32 v107, v99
	v_mov_b32_e32 v116, v99
	v_mov_b32_e32 v117, v99
	v_mov_b32_e32 v118, v99
	v_mov_b32_e32 v119, v99
	v_mov_b32_e32 v120, v99
	v_mov_b32_e32 v121, v99
	v_mov_b32_e32 v122, v99
	v_mov_b32_e32 v123, v99
	v_mov_b32_e32 v72, v99
	v_mov_b32_e32 v73, v99
	v_mov_b32_e32 v74, v99
	v_mov_b32_e32 v75, v99
	v_mov_b32_e32 v76, v99
	v_mov_b32_e32 v77, v99
	v_mov_b32_e32 v78, v99
	v_mov_b32_e32 v79, v99
	v_mov_b32_e32 v88, v99
	v_mov_b32_e32 v89, v99
	v_mov_b32_e32 v90, v99
	v_mov_b32_e32 v91, v99
	v_mov_b32_e32 v92, v99
	v_mov_b32_e32 v93, v99
	v_mov_b32_e32 v94, v99
	v_mov_b32_e32 v95, v99
	v_mov_b32_e32 v108, v99
	v_mov_b32_e32 v109, v99
	v_mov_b32_e32 v110, v99
	v_mov_b32_e32 v111, v99
	v_mov_b32_e32 v112, v99
	v_mov_b32_e32 v113, v99
	v_mov_b32_e32 v114, v99
	v_mov_b32_e32 v115, v99
	v_mov_b32_e32 v124, v99
	v_mov_b32_e32 v125, v99
	v_mov_b32_e32 v126, v99
	v_mov_b32_e32 v127, v99
	v_mov_b32_e32 v128, v99
	v_mov_b32_e32 v129, v99
	v_mov_b32_e32 v130, v99
	v_mov_b32_e32 v131, v99
	.p2align	6

; template <class Epi, class Sched, bool ALIGN_EPI = false, bool SP2 = false>
; __device__ __forceinline__ void gemm_phase(PG8_LAS unsigned char* lds, const Gemm g, const Sched& S, const Epi& E, const int tid_in) {
;     ...
;         const bool has_next = S.next(ui + 1, nxt);
;         const char* nA = has_next ? (const char*)g.A + (size_t)nxt.pm * tstepA : cA; const char* nB = has_next ? (const char*)g.Bt + (size_t)nxt.pn * tstepB : cB;
;         for (int t = 0; t < nt; t += 2) {
;             const bool last = (t == nt - 2);
;             const char* a1 = cA + (size_t)(t + 1) * kstep;
;             const char* a2 = last ? nA : cA + (size_t)(t + 2) * kstep; const char* b2 = last ? nB : cB + (size_t)(t + 2) * kstep;
;     ...
;         for (int a = 0; a < 2; ++a)
; #pragma unroll
;             for (int b = 0; b < 2; ++b)
; #pragma unroll
;                 for (int m = 0; m < 4; ++m)
; #pragma unroll
;                     for (int n = 0; n < 2; ++n) acc[a][b][m][n] = (f32x4){zf_, zf_, zf_, zf_};
;         cur = nxt; cA = nA; cB = nB; ++ui;
.LBB0_1130:
	s_ashr_i32 s15, s14, 31
	s_lshl_b64 s[16:17], s[14:15], 19
	s_add_u32 s16, s26, s16
	s_addc_u32 s17, s27, s17
	s_and_b64 s[18:19], s[8:9], exec
	s_cselect_b32 s15, s17, s21
	s_cselect_b32 s44, s16, s20
	s_ashr_i32 s13, s12, 31
	s_lshl_b64 s[18:19], s[12:13], 19
	s_add_u32 s18, s28, s18
	s_addc_u32 s19, s29, s19
	s_and_b64 s[24:25], s[8:9], exec
	s_cselect_b32 s13, s19, s23
	s_cselect_b32 s45, s18, s22
	s_add_u32 s20, s20, 0x40080
	s_addc_u32 s21, s21, 0
	s_add_u32 s46, s22, 0x100
	s_addc_u32 s47, s23, 0
	s_mov_b32 s48, -2
	v_mov_b32_e32 v0, v99
	v_mov_b32_e32 v1, v99
	v_mov_b32_e32 v2, v99
	v_mov_b32_e32 v3, v99
	v_mov_b32_e32 v4, v99
	v_mov_b32_e32 v5, v99
	v_mov_b32_e32 v6, v99
	v_mov_b32_e32 v7, v99
	v_mov_b32_e32 v16, v99
	v_mov_b32_e32 v17, v99
	v_mov_b32_e32 v18, v99
	v_mov_b32_e32 v19, v99
	v_mov_b32_e32 v20, v99
	v_mov_b32_e32 v21, v99
	v_mov_b32_e32 v22, v99
	v_mov_b32_e32 v23, v99
	v_mov_b32_e32 v32, v99
	v_mov_b32_e32 v33, v99
	v_mov_b32_e32 v34, v99
	v_mov_b32_e32 v35, v99
	v_mov_b32_e32 v36, v99
	v_mov_b32_e32 v37, v99
	v_mov_b32_e32 v38, v99
	v_mov_b32_e32 v39, v99
	v_mov_b32_e32 v48, v99
	v_mov_b32_e32 v49, v99
	v_mov_b32_e32 v50, v99
	v_mov_b32_e32 v51, v99
	v_mov_b32_e32 v52, v99
	v_mov_b32_e32 v53, v99
	v_mov_b32_e32 v54, v99
	v_mov_b32_e32 v55, v99
	v_mov_b32_e32 v8, v99
	v_mov_b32_e32 v9, v99
	v_mov_b32_e32 v10, v99
	v_mov_b32_e32 v11, v99
	v_mov_b32_e32 v12, v99
	v_mov_b32_e32 v13, v99
	v_mov_b32_e32 v14, v99
	v_mov_b32_e32 v15, v99
	v_mov_b32_e32 v24, v99
	v_mov_b32_e32 v25, v99
	v_mov_b32_e32 v26, v99
	v_mov_b32_e32 v27, v99
	v_mov_b32_e32 v28, v99
	v_mov_b32_e32 v29, v99
	v_mov_b32_e32 v30, v99
	v_mov_b32_e32 v31, v99
	v_mov_b32_e32 v40, v99
	v_mov_b32_e32 v41, v99
	v_mov_b32_e32 v42, v99
	v_mov_b32_e32 v43, v99
	v_mov_b32_e32 v44, v99
	v_mov_b32_e32 v45, v99
	v_mov_b32_e32 v46, v99
	v_mov_b32_e32 v47, v99
	v_mov_b32_e32 v56, v99
	v_mov_b32_e32 v57, v99
	v_mov_b32_e32 v58, v99
	v_mov_b32_e32 v59, v99
	v_mov_b32_e32 v60, v99
	v_mov_b32_e32 v61, v99
	v_mov_b32_e32 v62, v99
	v_mov_b32_e32 v63, v99
	v_mov_b32_e32 v64, v99
	v_mov_b32_e32 v65, v99
	v_mov_b32_e32 v66, v99
	v_mov_b32_e32 v67, v99
	v_mov_b32_e32 v68, v99
	v_mov_b32_e32 v69, v99
	v_mov_b32_e32 v70, v99
	v_mov_b32_e32 v71, v99
	v_mov_b32_e32 v80, v99
	v_mov_b32_e32 v81, v99
	v_mov_b32_e32 v82, v99
	v_mov_b32_e32 v83, v99
	v_mov_b32_e32 v84, v99
	v_mov_b32_e32 v85, v99
	v_mov_b32_e32 v86, v99
	v_mov_b32_e32 v87, v99
	v_mov_b32_e32 v100, v99
	v_mov_b32_e32 v101, v99
	v_mov_b32_e32 v102, v99
	v_mov_b32_e32 v103, v99
	v_mov_b32_e32 v104, v99
	v_mov_b32_e32 v105, v99
	v_mov_b32_e32 v106, v99
	v_mov_b32_e32 v107, v99
	v_mov_b32_e32 v116, v99
	v_mov_b32_e32 v117, v99
	v_mov_b32_e32 v118, v99
	v_mov_b32_e32 v119, v99
	v_mov_b32_e32 v120, v99
	v_mov_b32_e32 v121, v99
	v_mov_b32_e32 v122, v99
	v_mov_b32_e32 v123, v99
	v_mov_b32_e32 v72, v99
	v_mov_b32_e32 v73, v99
	v_mov_b32_e32 v74, v99
	v_mov_b32_e32 v75, v99
	v_mov_b32_e32 v76, v99
	v_mov_b32_e32 v77, v99
	v_mov_b32_e32 v78, v99
	v_mov_b32_e32 v79, v99
	v_mov_b32_e32 v88, v99
	v_mov_b32_e32 v89, v99
	v_mov_b32_e32 v90, v99
	v_mov_b32_e32 v91, v99
	v_mov_b32_e32 v92, v99
	v_mov_b32_e32 v93, v99
	v_mov_b32_e32 v94, v99
	v_mov_b32_e32 v95, v99
	v_mov_b32_e32 v108, v99
	v_mov_b32_e32 v109, v99
	v_mov_b32_e32 v110, v99
	v_mov_b32_e32 v111, v99
	v_mov_b32_e32 v112, v99
	v_mov_b32_e32 v113, v99
	v_mov_b32_e32 v114, v99
	v_mov_b32_e32 v115, v99
	v_mov_b32_e32 v124, v99
	v_mov_b32_e32 v125, v99
	v_mov_b32_e32 v126, v99
	v_mov_b32_e32 v127, v99
	v_mov_b32_e32 v128, v99
	v_mov_b32_e32 v129, v99
	v_mov_b32_e32 v130, v99
	v_mov_b32_e32 v131, v99
	.p2align	6
